# attention O outputs (read once, in P4) stored with nt
# baseline (speedup 1.0000x reference)
.LBB0_848:
	s_or_b64 exec, exec, s[0:1]
	v_cmp_lt_i32_e32 vcc, v27, v28
	s_movk_i32 s0, 0x80
	s_nop 0
	v_cndmask_b32_e32 v0, v26, v27, vcc
	v_lshlrev_b32_e32 v0, 2, v0
	ds_bpermute_b32 v0, v0, v51
	v_cmp_lt_i32_e32 vcc, v29, v28
	s_waitcnt lgkmcnt(0)
	v_add_f32_e32 v0, v51, v0
	v_cndmask_b32_e32 v1, v26, v29, vcc
	v_lshlrev_b32_e32 v1, 2, v1
	ds_bpermute_b32 v1, v1, v0
	v_cmp_gt_i32_e32 vcc, s0, v42
	s_and_saveexec_b64 s[0:1], vcc
	s_cbranch_execz .LBB0_850
	s_lshl_b64 s[2:3], s[2:3], 11
	v_readlane_b32 s8, v254, 1
	v_readlane_b32 s9, v254, 2
	s_add_u32 s4, s8, s2
	s_addc_u32 s5, s9, s3
	s_add_u32 s4, s4, s6
	v_ashrrev_i32_e32 v43, 31, v42
	s_addc_u32 s5, s5, 0
	v_lshlrev_b64 v[2:3], 11, v[42:43]
	v_lshl_add_u64 v[4:5], s[4:5], 0, v[2:3]
	v_lshlrev_b32_e32 v16, 1, v45
	v_lshl_add_u64 v[4:5], v[4:5], 0, v[16:17]
	global_load_dwordx2 v[6:7], v[4:5], off offset:1536
	global_load_dwordx2 v[26:27], v[4:5], off offset:1568
	global_load_dwordx2 v[28:29], v[4:5], off offset:1600
	s_nop 0
	global_load_dwordx2 v[4:5], v[4:5], off offset:1632
	s_waitcnt lgkmcnt(0)
	v_add_f32_e32 v30, v0, v1
	v_div_scale_f32 v31, s[4:5], v30, v30, 1.0
	v_rcp_f32_e32 v32, v31
	v_readlane_b32 s10, v254, 3
	v_readlane_b32 s11, v254, 4
	v_readlane_b32 s8, v254, 19
	v_readlane_b32 s10, v254, 21
	v_fma_f32 v0, -v31, v32, 1.0
	v_div_scale_f32 v33, vcc, 1.0, v30, 1.0
	v_readlane_b32 s11, v254, 22
	s_add_u32 s2, s10, s2
	v_fmac_f32_e32 v32, v0, v32
	s_addc_u32 s3, s11, s3
	v_mul_f32_e32 v34, v33, v32
	s_add_u32 s2, s2, s6
	v_fma_f32 v35, -v31, v34, v33
	s_addc_u32 s3, s3, 0
	v_fmac_f32_e32 v34, v35, v32
	v_lshl_add_u64 v[0:1], s[2:3], 0, v[2:3]
	v_fma_f32 v2, -v31, v34, v33
	v_div_fmas_f32 v2, v2, v32, v34
	v_div_fixup_f32 v2, v2, v30, 1.0
	v_lshl_add_u64 v[0:1], v[0:1], 0, v[16:17]
	v_mul_f32_e32 v3, v8, v2
	v_mul_f32_e32 v8, v9, v2
	v_mul_f32_e32 v9, v10, v2
	v_mul_f32_e32 v10, v11, v2
	v_mul_f32_e32 v11, v12, v2
	v_mul_f32_e32 v12, v13, v2
	v_mul_f32_e32 v13, v14, v2
	v_mul_f32_e32 v14, v15, v2
	v_mul_f32_e32 v15, v18, v2
	v_mul_f32_e32 v16, v19, v2
	v_mul_f32_e32 v18, v20, v2
	v_mul_f32_e32 v19, v21, v2
	v_mul_f32_e32 v20, v22, v2
	v_mul_f32_e32 v21, v23, v2
	v_mul_f32_e32 v22, v24, v2
	v_mul_f32_e32 v23, v25, v2
	v_readlane_b32 s12, v254, 5
	v_readlane_b32 s13, v254, 6
	v_readlane_b32 s14, v254, 7
	v_readlane_b32 s15, v254, 8
	v_readlane_b32 s16, v254, 9
	v_readlane_b32 s17, v254, 10
	v_readlane_b32 s18, v254, 11
	v_readlane_b32 s19, v254, 12
	v_readlane_b32 s20, v254, 13
	v_readlane_b32 s21, v254, 14
	v_readlane_b32 s22, v254, 15
	v_readlane_b32 s23, v254, 16
	v_readlane_b32 s9, v254, 20
	s_waitcnt vmcnt(3)
	v_lshlrev_b32_e32 v2, 16, v6
	v_and_b32_e32 v6, 0xffff0000, v6
	v_lshlrev_b32_e32 v24, 16, v7
	v_and_b32_e32 v7, 0xffff0000, v7
	s_waitcnt vmcnt(2)
	v_lshlrev_b32_e32 v25, 16, v26
	v_and_b32_e32 v26, 0xffff0000, v26
	v_mul_f32_e32 v2, v3, v2
	v_mul_f32_e32 v3, v8, v6
	v_lshlrev_b32_e32 v30, 16, v27
	v_and_b32_e32 v27, 0xffff0000, v27
	s_waitcnt vmcnt(1)
	v_lshlrev_b32_e32 v31, 16, v28
	v_and_b32_e32 v28, 0xffff0000, v28
	v_lshlrev_b32_e32 v32, 16, v29
	v_and_b32_e32 v29, 0xffff0000, v29
	s_waitcnt vmcnt(0)
	v_lshlrev_b32_e32 v33, 16, v4
	v_and_b32_e32 v4, 0xffff0000, v4
	v_mul_f32_e32 v6, v9, v24
	v_mul_f32_e32 v7, v10, v7
	v_mul_f32_e32 v8, v11, v25
	v_mul_f32_e32 v9, v12, v26
	v_cvt_pk_bf16_f32 v2, v2, v3
	v_cvt_pk_bf16_f32 v3, v6, v7
	v_lshlrev_b32_e32 v34, 16, v5
	v_mul_f32_e32 v10, v13, v30
	v_mul_f32_e32 v11, v14, v27
	v_mul_f32_e32 v12, v15, v31
	v_mul_f32_e32 v13, v16, v28
	v_mul_f32_e32 v14, v18, v32
	v_mul_f32_e32 v15, v19, v29
	v_mul_f32_e32 v4, v21, v4
	v_cvt_pk_bf16_f32 v6, v8, v9
	v_cvt_pk_bf16_f32 v7, v10, v11
	v_cvt_pk_bf16_f32 v8, v12, v13
	v_cvt_pk_bf16_f32 v9, v14, v15
	global_store_dwordx2 v[0:1], v[2:3], off offset:1536 nt
	global_store_dwordx2 v[0:1], v[6:7], off offset:1568 nt
	global_store_dwordx2 v[0:1], v[8:9], off offset:1600 nt
	v_and_b32_e32 v2, 0xffff0000, v5
	v_mul_f32_e32 v16, v20, v33
	v_mul_f32_e32 v18, v22, v34
	v_cvt_pk_bf16_f32 v4, v16, v4
	v_mul_f32_e32 v2, v23, v2
	v_cvt_pk_bf16_f32 v5, v18, v2
	global_store_dwordx2 v[0:1], v[4:5], off offset:1632 nt

.LBB0_1040:
	s_waitcnt vmcnt(1)
	v_mbcnt_hi_u32_b32 v1, -1, v204
	v_and_b32_e32 v2, 64, v1
	v_xor_b32_e32 v0, 16, v1
	v_add_u32_e32 v2, 64, v2
	v_cmp_lt_i32_e32 vcc, v0, v2
	v_xor_b32_e32 v3, 32, v1
	s_movk_i32 s0, 0x80
	v_cndmask_b32_e32 v0, v1, v0, vcc
	v_lshlrev_b32_e32 v0, 2, v0
	ds_bpermute_b32 v0, v0, v83
	v_cmp_lt_i32_e32 vcc, v3, v2
	s_waitcnt lgkmcnt(0)
	v_add_f32_e32 v0, v83, v0
	v_cndmask_b32_e32 v1, v1, v3, vcc
	v_lshlrev_b32_e32 v1, 2, v1
	ds_bpermute_b32 v1, v1, v0
	v_cmp_gt_i32_e32 vcc, s0, v44
	s_and_saveexec_b64 s[0:1], vcc
	s_cbranch_execz .LBB0_1042
	s_lshl_b32 s4, s14, 11
	v_readlane_b32 s16, v254, 1
	v_readlane_b32 s17, v254, 2
	s_add_u32 s2, s16, s4
	s_addc_u32 s3, s17, 0
	s_lshl_b32 s5, s15, 1
	s_add_u32 s2, s2, s5
	v_ashrrev_i32_e32 v45, 31, v44
	s_addc_u32 s3, s3, 0
	v_lshlrev_b64 v[2:3], 11, v[44:45]
	s_waitcnt vmcnt(0)
	v_lshl_add_u64 v[4:5], s[2:3], 0, v[2:3]
	v_lshlrev_b32_e32 v16, 1, v66
	v_lshl_add_u64 v[4:5], v[4:5], 0, v[16:17]
	global_load_dwordx2 v[6:7], v[4:5], off
	global_load_dwordx2 v[8:9], v[4:5], off offset:32
	global_load_dwordx2 v[10:11], v[4:5], off offset:64
	s_nop 0
	global_load_dwordx2 v[4:5], v[4:5], off offset:96
	s_waitcnt lgkmcnt(0)
	v_add_f32_e32 v12, v0, v1
	v_div_scale_f32 v13, s[2:3], v12, v12, 1.0
	v_rcp_f32_e32 v14, v13
	v_readlane_b32 s8, v254, 19
	v_readlane_b32 s10, v254, 21
	v_div_scale_f32 v15, vcc, 1.0, v12, 1.0
	v_fma_f32 v0, -v13, v14, 1.0
	v_readlane_b32 s11, v254, 22
	s_add_u32 s2, s10, s4
	v_fmac_f32_e32 v14, v0, v14
	s_addc_u32 s3, s11, 0
	v_mul_f32_e32 v18, v15, v14
	s_add_u32 s2, s2, s5
	v_fma_f32 v19, -v13, v18, v15
	s_addc_u32 s3, s3, 0
	v_fmac_f32_e32 v18, v19, v14
	v_lshl_add_u64 v[0:1], s[2:3], 0, v[2:3]
	v_fma_f32 v2, -v13, v18, v15
	v_div_fmas_f32 v2, v2, v14, v18
	v_div_fixup_f32 v12, v2, v12, 1.0
	v_mul_f32_e32 v2, v28, v12
	v_mul_f32_e32 v3, v29, v12
	v_lshl_add_u64 v[0:1], v[0:1], 0, v[16:17]
	v_mul_f32_e32 v13, v30, v12
	v_mul_f32_e32 v14, v31, v12
	v_mul_f32_e32 v16, v37, v12
	v_mul_f32_e32 v19, v39, v12
	v_mul_f32_e32 v15, v36, v12
	v_mul_f32_e32 v18, v38, v12
	v_mul_f32_e32 v20, v40, v12
	v_mul_f32_e32 v21, v41, v12
	v_mul_f32_e32 v22, v42, v12
	v_mul_f32_e32 v23, v43, v12
	v_mul_f32_e32 v24, v32, v12
	v_mul_f32_e32 v25, v33, v12
	v_mul_f32_e32 v26, v34, v12
	v_readlane_b32 s18, v254, 3
	v_readlane_b32 s19, v254, 4
	v_readlane_b32 s20, v254, 5
	v_readlane_b32 s21, v254, 6
	v_readlane_b32 s22, v254, 7
	v_readlane_b32 s23, v254, 8
	v_readlane_b32 s24, v254, 9
	v_readlane_b32 s25, v254, 10
	v_readlane_b32 s26, v254, 11
	v_readlane_b32 s27, v254, 12
	v_readlane_b32 s28, v254, 13
	v_readlane_b32 s29, v254, 14
	v_readlane_b32 s30, v254, 15
	v_readlane_b32 s31, v254, 16
	v_readlane_b32 s9, v254, 20
	s_waitcnt vmcnt(3)
	v_lshlrev_b32_e32 v27, 16, v6
	v_and_b32_e32 v6, 0xffff0000, v6
	v_lshlrev_b32_e32 v28, 16, v7
	v_and_b32_e32 v7, 0xffff0000, v7
	s_waitcnt vmcnt(2)
	v_lshlrev_b32_e32 v29, 16, v8
	v_and_b32_e32 v8, 0xffff0000, v8
	v_lshlrev_b32_e32 v30, 16, v9
	v_and_b32_e32 v9, 0xffff0000, v9
	v_mul_f32_e32 v2, v2, v27
	v_mul_f32_e32 v3, v3, v6
	s_waitcnt vmcnt(1)
	v_lshlrev_b32_e32 v31, 16, v10
	v_and_b32_e32 v10, 0xffff0000, v10
	v_lshlrev_b32_e32 v32, 16, v11
	v_and_b32_e32 v11, 0xffff0000, v11
	s_waitcnt vmcnt(0)
	v_lshlrev_b32_e32 v33, 16, v4
	v_and_b32_e32 v4, 0xffff0000, v4
	v_mul_f32_e32 v6, v13, v28
	v_mul_f32_e32 v7, v14, v7
	v_mul_f32_e32 v8, v16, v8
	v_mul_f32_e32 v9, v19, v9
	v_cvt_pk_bf16_f32 v2, v2, v3
	v_cvt_pk_bf16_f32 v3, v6, v7
	v_lshlrev_b32_e32 v34, 16, v5
	v_mul_f32_e32 v13, v15, v29
	v_mul_f32_e32 v14, v18, v30
	v_mul_f32_e32 v15, v20, v31
	v_mul_f32_e32 v10, v21, v10
	v_mul_f32_e32 v16, v22, v32
	v_mul_f32_e32 v11, v23, v11
	v_mul_f32_e32 v4, v25, v4
	v_cvt_pk_bf16_f32 v6, v13, v8
	v_cvt_pk_bf16_f32 v7, v14, v9
	v_cvt_pk_bf16_f32 v8, v15, v10
	v_cvt_pk_bf16_f32 v9, v16, v11
	global_store_dwordx2 v[0:1], v[2:3], off nt
	global_store_dwordx2 v[0:1], v[6:7], off offset:32 nt
	global_store_dwordx2 v[0:1], v[8:9], off offset:64 nt
	v_mul_f32_e32 v2, v35, v12
	v_and_b32_e32 v3, 0xffff0000, v5
	v_mul_f32_e32 v18, v24, v33
	v_mul_f32_e32 v19, v26, v34
	v_cvt_pk_bf16_f32 v4, v18, v4
	v_mul_f32_e32 v2, v2, v3
	v_cvt_pk_bf16_f32 v5, v19, v2
	global_store_dwordx2 v[0:1], v[4:5], off offset:96 nt

.LBB0_1304:
	s_or_b64 exec, exec, s[0:1]
	v_cmp_lt_i32_e32 vcc, v29, v28
	s_nop 1
	v_cndmask_b32_e32 v0, v26, v29, vcc
	v_lshlrev_b32_e32 v0, 2, v0
	ds_bpermute_b32 v0, v0, v51
	v_cmp_lt_i32_e32 vcc, v27, v28
	s_waitcnt lgkmcnt(0)
	v_add_f32_e32 v0, v51, v0
	v_cndmask_b32_e32 v1, v26, v27, vcc
	v_lshlrev_b32_e32 v1, 2, v1
	ds_bpermute_b32 v1, v1, v0
	v_cmp_gt_i32_e32 vcc, 32, v42
	s_and_saveexec_b64 s[0:1], vcc
	s_cbranch_execz .LBB0_1306
	v_readlane_b32 s2, v254, 51
	v_readlane_b32 s3, v254, 52
	s_lshl_b64 s[2:3], s[2:3], 16
	v_readlane_b32 s8, v254, 29
	v_readlane_b32 s9, v254, 30
	s_add_u32 s5, s8, s2
	s_addc_u32 s7, s9, s3
	s_add_u32 s6, s5, s4
	v_ashrrev_i32_e32 v43, 31, v42
	s_addc_u32 s7, s7, 0
	v_lshlrev_b64 v[2:3], 11, v[42:43]
	v_lshl_add_u64 v[4:5], s[6:7], 0, v[2:3]
	v_lshlrev_b32_e32 v16, 1, v45
	v_lshl_add_u64 v[4:5], v[4:5], 0, v[16:17]
	global_load_dwordx2 v[6:7], v[4:5], off offset:1536
	global_load_dwordx2 v[26:27], v[4:5], off offset:1568
	global_load_dwordx2 v[28:29], v[4:5], off offset:1600
	s_nop 0
	global_load_dwordx2 v[4:5], v[4:5], off offset:1632
	s_waitcnt lgkmcnt(0)
	v_add_f32_e32 v30, v0, v1
	v_div_scale_f32 v31, s[6:7], v30, v30, 1.0
	v_rcp_f32_e32 v32, v31
	v_readlane_b32 s6, v254, 17
	v_div_scale_f32 v33, vcc, 1.0, v30, 1.0
	v_fma_f32 v0, -v31, v32, 1.0
	v_readlane_b32 s7, v254, 18
	s_add_u32 s2, s6, s2
	v_fmac_f32_e32 v32, v0, v32
	s_addc_u32 s3, s7, s3
	v_mul_f32_e32 v34, v33, v32
	s_add_u32 s2, s2, s4
	v_fma_f32 v35, -v31, v34, v33
	s_addc_u32 s3, s3, 0
	v_fmac_f32_e32 v34, v35, v32
	v_lshl_add_u64 v[0:1], s[2:3], 0, v[2:3]
	v_fma_f32 v2, -v31, v34, v33
	v_div_fmas_f32 v2, v2, v32, v34
	v_div_fixup_f32 v2, v2, v30, 1.0
	v_lshl_add_u64 v[0:1], v[0:1], 0, v[16:17]
	v_mul_f32_e32 v3, v8, v2
	v_mul_f32_e32 v8, v9, v2
	v_mul_f32_e32 v9, v10, v2
	v_mul_f32_e32 v10, v11, v2
	v_mul_f32_e32 v11, v12, v2
	v_mul_f32_e32 v12, v13, v2
	v_mul_f32_e32 v13, v14, v2
	v_mul_f32_e32 v14, v15, v2
	v_mul_f32_e32 v15, v18, v2
	v_mul_f32_e32 v16, v19, v2
	v_mul_f32_e32 v18, v20, v2
	v_mul_f32_e32 v19, v21, v2
	v_mul_f32_e32 v20, v22, v2
	v_mul_f32_e32 v21, v23, v2
	v_mul_f32_e32 v22, v24, v2
	v_mul_f32_e32 v23, v25, v2
	v_readlane_b32 s10, v254, 31
	v_readlane_b32 s11, v254, 32
	v_readlane_b32 s12, v254, 33
	v_readlane_b32 s13, v254, 34
	v_readlane_b32 s14, v254, 35
	v_readlane_b32 s15, v254, 36
	v_readlane_b32 s16, v254, 37
	v_readlane_b32 s17, v254, 38
	v_readlane_b32 s18, v254, 39
	v_readlane_b32 s19, v254, 40
	v_readlane_b32 s20, v254, 41
	v_readlane_b32 s21, v254, 42
	v_readlane_b32 s22, v254, 43
	v_readlane_b32 s23, v254, 44
	s_waitcnt vmcnt(3)
	v_lshlrev_b32_e32 v2, 16, v6
	v_and_b32_e32 v6, 0xffff0000, v6
	v_lshlrev_b32_e32 v24, 16, v7
	v_and_b32_e32 v7, 0xffff0000, v7
	s_waitcnt vmcnt(2)
	v_lshlrev_b32_e32 v25, 16, v26
	v_and_b32_e32 v26, 0xffff0000, v26
	v_mul_f32_e32 v2, v3, v2
	v_mul_f32_e32 v3, v8, v6
	v_lshlrev_b32_e32 v30, 16, v27
	v_and_b32_e32 v27, 0xffff0000, v27
	s_waitcnt vmcnt(1)
	v_lshlrev_b32_e32 v31, 16, v28
	v_and_b32_e32 v28, 0xffff0000, v28
	v_lshlrev_b32_e32 v32, 16, v29
	v_and_b32_e32 v29, 0xffff0000, v29
	s_waitcnt vmcnt(0)
	v_lshlrev_b32_e32 v33, 16, v4
	v_and_b32_e32 v4, 0xffff0000, v4
	v_mul_f32_e32 v6, v9, v24
	v_mul_f32_e32 v7, v10, v7
	v_mul_f32_e32 v8, v11, v25
	v_mul_f32_e32 v9, v12, v26
	v_cvt_pk_bf16_f32 v2, v2, v3
	v_cvt_pk_bf16_f32 v3, v6, v7
	v_lshlrev_b32_e32 v34, 16, v5
	v_mul_f32_e32 v10, v13, v30
	v_mul_f32_e32 v11, v14, v27
	v_mul_f32_e32 v12, v15, v31
	v_mul_f32_e32 v13, v16, v28
	v_mul_f32_e32 v14, v18, v32
	v_mul_f32_e32 v15, v19, v29
	v_mul_f32_e32 v4, v21, v4
	v_cvt_pk_bf16_f32 v6, v8, v9
	v_cvt_pk_bf16_f32 v7, v10, v11
	v_cvt_pk_bf16_f32 v8, v12, v13
	v_cvt_pk_bf16_f32 v9, v14, v15
	global_store_dwordx2 v[0:1], v[2:3], off offset:1536 nt
	global_store_dwordx2 v[0:1], v[6:7], off offset:1568 nt
	global_store_dwordx2 v[0:1], v[8:9], off offset:1600 nt
	v_and_b32_e32 v2, 0xffff0000, v5
	v_mul_f32_e32 v16, v20, v33
	v_mul_f32_e32 v18, v22, v34
	v_cvt_pk_bf16_f32 v4, v16, v4
	v_mul_f32_e32 v2, v23, v2
	v_cvt_pk_bf16_f32 v5, v18, v2
	global_store_dwordx2 v[0:1], v[4:5], off offset:1632 nt

.LBB0_1336:
	v_cmp_lt_i32_e32 vcc, v71, v72
	s_nop 1
	v_cndmask_b32_e32 v0, v133, v71, vcc
	v_lshlrev_b32_e32 v0, 2, v0
	ds_bpermute_b32 v0, v0, v86
	v_cmp_lt_i32_e32 vcc, v73, v72
	s_waitcnt lgkmcnt(0)
	v_add_f32_e32 v0, v86, v0
	v_cndmask_b32_e32 v1, v133, v73, vcc
	v_lshlrev_b32_e32 v1, 2, v1
	ds_bpermute_b32 v1, v1, v0
	v_cmp_gt_i32_e32 vcc, 32, v48
	s_and_saveexec_b64 s[0:1], vcc
	s_cbranch_execz .LBB0_1338
	s_lshl_b32 s4, s10, 16
	v_readlane_b32 s12, v254, 29
	v_readlane_b32 s13, v254, 30
	s_add_u32 s2, s12, s4
	s_addc_u32 s3, s13, 0
	s_add_u32 s2, s2, s8
	v_ashrrev_i32_e32 v49, 31, v48
	s_addc_u32 s3, s3, 0
	v_lshlrev_b64 v[2:3], 11, v[48:49]
	v_lshl_add_u64 v[4:5], s[2:3], 0, v[2:3]
	v_lshlrev_b32_e32 v16, 1, v80
	v_lshl_add_u64 v[4:5], v[4:5], 0, v[16:17]
	global_load_dwordx2 v[6:7], v[4:5], off
	global_load_dwordx2 v[8:9], v[4:5], off offset:32
	global_load_dwordx2 v[10:11], v[4:5], off offset:64
	s_nop 0
	global_load_dwordx2 v[4:5], v[4:5], off offset:96
	s_waitcnt vmcnt(5) lgkmcnt(0)
	v_add_f32_e32 v12, v0, v1
	v_div_scale_f32 v13, s[2:3], v12, v12, 1.0
	v_rcp_f32_e32 v14, v13
	v_readlane_b32 s2, v254, 17
	v_div_scale_f32 v15, vcc, 1.0, v12, 1.0
	v_fma_f32 v0, -v13, v14, 1.0
	v_readlane_b32 s3, v254, 18
	s_add_u32 s2, s2, s4
	v_fmac_f32_e32 v14, v0, v14
	s_addc_u32 s3, s3, 0
	v_mul_f32_e32 v18, v15, v14
	s_add_u32 s2, s2, s8
	v_fma_f32 v19, -v13, v18, v15
	s_addc_u32 s3, s3, 0
	v_fmac_f32_e32 v18, v19, v14
	v_lshl_add_u64 v[0:1], s[2:3], 0, v[2:3]
	v_fma_f32 v2, -v13, v18, v15
	v_div_fmas_f32 v2, v2, v14, v18
	v_div_fixup_f32 v2, v2, v12, 1.0
	v_lshl_add_u64 v[0:1], v[0:1], 0, v[16:17]
	v_mul_f32_e32 v3, v28, v2
	v_mul_f32_e32 v12, v29, v2
	v_mul_f32_e32 v13, v30, v2
	v_mul_f32_e32 v14, v31, v2
	v_mul_f32_e32 v15, v32, v2
	v_mul_f32_e32 v16, v33, v2
	v_mul_f32_e32 v18, v34, v2
	v_mul_f32_e32 v19, v35, v2
	s_waitcnt vmcnt(4)
	v_mul_f32_e32 v20, v36, v2
	v_mul_f32_e32 v21, v37, v2
	v_mul_f32_e32 v22, v38, v2
	v_mul_f32_e32 v23, v39, v2
	v_mul_f32_e32 v24, v40, v2
	v_mul_f32_e32 v25, v41, v2
	v_mul_f32_e32 v26, v42, v2
	v_mul_f32_e32 v27, v43, v2
	v_readlane_b32 s14, v254, 31
	v_readlane_b32 s15, v254, 32
	v_readlane_b32 s16, v254, 33
	v_readlane_b32 s17, v254, 34
	v_readlane_b32 s18, v254, 35
	v_readlane_b32 s19, v254, 36
	v_readlane_b32 s20, v254, 37
	v_readlane_b32 s21, v254, 38
	v_readlane_b32 s22, v254, 39
	v_readlane_b32 s23, v254, 40
	v_readlane_b32 s24, v254, 41
	v_readlane_b32 s25, v254, 42
	v_readlane_b32 s26, v254, 43
	v_readlane_b32 s27, v254, 44
	s_waitcnt vmcnt(3)
	v_lshlrev_b32_e32 v2, 16, v6
	v_and_b32_e32 v6, 0xffff0000, v6
	v_lshlrev_b32_e32 v28, 16, v7
	v_and_b32_e32 v7, 0xffff0000, v7
	s_waitcnt vmcnt(2)
	v_lshlrev_b32_e32 v29, 16, v8
	v_and_b32_e32 v8, 0xffff0000, v8
	v_lshlrev_b32_e32 v30, 16, v9
	v_and_b32_e32 v9, 0xffff0000, v9
	v_mul_f32_e32 v2, v3, v2
	v_mul_f32_e32 v3, v12, v6
	s_waitcnt vmcnt(1)
	v_lshlrev_b32_e32 v31, 16, v10
	v_and_b32_e32 v10, 0xffff0000, v10
	v_lshlrev_b32_e32 v32, 16, v11
	v_and_b32_e32 v11, 0xffff0000, v11
	s_waitcnt vmcnt(0)
	v_lshlrev_b32_e32 v33, 16, v4
	v_and_b32_e32 v4, 0xffff0000, v4
	v_mul_f32_e32 v6, v13, v28
	v_mul_f32_e32 v7, v14, v7
	v_mul_f32_e32 v8, v16, v8
	v_mul_f32_e32 v9, v19, v9
	v_cvt_pk_bf16_f32 v2, v2, v3
	v_cvt_pk_bf16_f32 v3, v6, v7
	v_lshlrev_b32_e32 v34, 16, v5
	v_mul_f32_e32 v12, v15, v29
	v_mul_f32_e32 v13, v18, v30
	v_mul_f32_e32 v14, v20, v31
	v_mul_f32_e32 v10, v21, v10
	v_mul_f32_e32 v15, v22, v32
	v_mul_f32_e32 v11, v23, v11
	v_mul_f32_e32 v4, v25, v4
	v_cvt_pk_bf16_f32 v6, v12, v8
	v_cvt_pk_bf16_f32 v7, v13, v9
	v_cvt_pk_bf16_f32 v8, v14, v10
	v_cvt_pk_bf16_f32 v9, v15, v11
	global_store_dwordx2 v[0:1], v[2:3], off nt
	global_store_dwordx2 v[0:1], v[6:7], off offset:32 nt
	global_store_dwordx2 v[0:1], v[8:9], off offset:64 nt
	v_and_b32_e32 v2, 0xffff0000, v5
	v_mul_f32_e32 v16, v24, v33
	v_mul_f32_e32 v18, v26, v34
	v_cvt_pk_bf16_f32 v4, v16, v4
	v_mul_f32_e32 v2, v27, v2
	v_cvt_pk_bf16_f32 v5, v18, v2
	global_store_dwordx2 v[0:1], v[4:5], off offset:96 nt

.LBB0_1695:
	v_cmp_lt_i32_e32 vcc, v87, v88
	s_nop 1
	v_cndmask_b32_e32 v0, v133, v87, vcc
	v_lshlrev_b32_e32 v0, 2, v0
	ds_bpermute_b32 v0, v0, v83
	v_cmp_lt_i32_e32 vcc, v89, v88
	s_waitcnt lgkmcnt(0)
	v_add_f32_e32 v0, v83, v0
	v_cndmask_b32_e32 v1, v133, v89, vcc
	v_lshlrev_b32_e32 v1, 2, v1
	ds_bpermute_b32 v1, v1, v0
	s_and_saveexec_b64 s[0:1], s[8:9]
	s_cbranch_execz .LBB0_1697
	s_lshl_b64 s[2:3], s[60:61], 11
	s_add_u32 s4, s50, s2
	s_addc_u32 s5, s51, s3
	s_add_u32 s2, s40, s2
	s_addc_u32 s3, s41, s3
	s_lshl_b32 s6, s84, 1
	s_add_u32 s2, s2, s6
	s_addc_u32 s3, s3, 0
	s_add_u32 s4, s4, s6
	v_ashrrev_i32_e32 v57, 31, v56
	s_addc_u32 s5, s5, 0
	v_lshlrev_b64 v[2:3], 11, v[56:57]
	v_lshl_add_u64 v[4:5], s[4:5], 0, v[2:3]
	v_lshlrev_b32_e32 v64, 1, v72
	v_lshl_add_u64 v[4:5], v[4:5], 0, v[64:65]
	global_load_dwordx2 v[6:7], v[4:5], off offset:768
	global_load_dwordx2 v[8:9], v[4:5], off offset:800
	global_load_dwordx2 v[10:11], v[4:5], off offset:832
	s_nop 0
	global_load_dwordx2 v[4:5], v[4:5], off offset:864
	s_waitcnt lgkmcnt(0)
	v_add_f32_e32 v12, v0, v1
	v_div_scale_f32 v13, s[4:5], v12, v12, 1.0
	v_rcp_f32_e32 v14, v13
	v_div_scale_f32 v15, vcc, 1.0, v12, 1.0
	v_fma_f32 v0, -v13, v14, 1.0
	v_fmac_f32_e32 v14, v0, v14
	v_lshl_add_u64 v[0:1], s[2:3], 0, v[2:3]
	v_mul_f32_e32 v2, v15, v14
	v_fma_f32 v3, -v13, v2, v15
	v_fmac_f32_e32 v2, v3, v14
	v_fma_f32 v3, -v13, v2, v15
	v_div_fmas_f32 v2, v3, v14, v2
	v_div_fixup_f32 v2, v2, v12, 1.0
	v_mul_f32_e32 v3, v52, v2
	v_mul_f32_e32 v23, v24, v2
	v_mul_f32_e32 v24, v25, v2
	v_mul_f32_e32 v25, v26, v2
	v_mul_f32_e32 v12, v53, v2
	v_mul_f32_e32 v13, v54, v2
	v_mul_f32_e32 v14, v55, v2
	v_mul_f32_e32 v15, v48, v2
	v_mul_f32_e32 v16, v49, v2
	v_mul_f32_e32 v17, v50, v2
	v_mul_f32_e32 v18, v51, v2
	v_mul_f32_e32 v19, v44, v2
	v_mul_f32_e32 v20, v45, v2
	v_mul_f32_e32 v21, v46, v2
	v_mul_f32_e32 v22, v47, v2
	v_mul_f32_e32 v2, v27, v2
	v_lshl_add_u64 v[0:1], v[0:1], 0, v[64:65]
	s_waitcnt vmcnt(3)
	v_lshlrev_b32_e32 v26, 16, v6
	v_and_b32_e32 v6, 0xffff0000, v6
	v_lshlrev_b32_e32 v27, 16, v7
	v_and_b32_e32 v7, 0xffff0000, v7
	s_waitcnt vmcnt(2)
	v_lshlrev_b32_e32 v28, 16, v8
	v_and_b32_e32 v8, 0xffff0000, v8
	v_lshlrev_b32_e32 v29, 16, v9
	v_and_b32_e32 v9, 0xffff0000, v9
	s_waitcnt vmcnt(1)
	v_lshlrev_b32_e32 v30, 16, v10
	v_and_b32_e32 v10, 0xffff0000, v10
	s_waitcnt vmcnt(0)
	v_lshlrev_b32_e32 v33, 16, v5
	v_and_b32_e32 v5, 0xffff0000, v5
	v_mul_f32_e32 v3, v3, v26
	v_lshlrev_b32_e32 v31, 16, v11
	v_and_b32_e32 v11, 0xffff0000, v11
	v_lshlrev_b32_e32 v32, 16, v4
	v_and_b32_e32 v4, 0xffff0000, v4
	v_mul_f32_e32 v6, v12, v6
	v_mul_f32_e32 v12, v13, v27
	v_mul_f32_e32 v7, v14, v7
	v_mul_f32_e32 v8, v16, v8
	v_mul_f32_e32 v9, v18, v9
	v_mul_f32_e32 v10, v20, v10
	v_mul_f32_e32 v20, v2, v5
	v_cvt_pk_bf16_f32 v2, v3, v6
	v_cvt_pk_bf16_f32 v3, v12, v7
	v_mul_f32_e32 v13, v15, v28
	v_mul_f32_e32 v14, v17, v29
	v_mul_f32_e32 v15, v19, v30
	v_mul_f32_e32 v16, v21, v31
	v_mul_f32_e32 v11, v22, v11
	v_mul_f32_e32 v17, v23, v32
	v_mul_f32_e32 v18, v24, v4
	v_mul_f32_e32 v19, v25, v33
	v_cvt_pk_bf16_f32 v4, v13, v8
	v_cvt_pk_bf16_f32 v5, v14, v9
	v_cvt_pk_bf16_f32 v6, v15, v10
	v_cvt_pk_bf16_f32 v7, v16, v11
	v_cvt_pk_bf16_f32 v8, v17, v18
	v_cvt_pk_bf16_f32 v9, v19, v20
	global_store_dwordx2 v[0:1], v[2:3], off offset:768 nt
	global_store_dwordx2 v[0:1], v[4:5], off offset:800 nt
	global_store_dwordx2 v[0:1], v[6:7], off offset:832 nt
	global_store_dwordx2 v[0:1], v[8:9], off offset:864 nt

.LBB0_1724:
	v_cmp_lt_i32_e32 vcc, v87, v88
	s_nop 1
	v_cndmask_b32_e32 v0, v133, v87, vcc
	v_lshlrev_b32_e32 v0, 2, v0
	ds_bpermute_b32 v0, v0, v104
	v_cmp_lt_i32_e32 vcc, v89, v88
	s_waitcnt lgkmcnt(0)
	v_add_f32_e32 v0, v104, v0
	v_cndmask_b32_e32 v1, v133, v89, vcc
	v_lshlrev_b32_e32 v1, 2, v1
	ds_bpermute_b32 v1, v1, v0
	s_and_saveexec_b64 s[0:1], s[8:9]
	s_cbranch_execz .LBB0_1726
	s_lshl_b64 s[2:3], s[18:19], 16
	s_add_u32 s4, s58, s2
	s_addc_u32 s5, s59, s3
	s_add_u32 s2, s42, s2
	s_addc_u32 s3, s43, s3
	s_add_u32 s2, s2, s20
	s_addc_u32 s3, s3, s21
	s_add_u32 s4, s4, s20
	v_ashrrev_i32_e32 v67, 31, v66
	s_addc_u32 s5, s5, s21
	v_lshlrev_b64 v[2:3], 11, v[66:67]
	v_lshl_add_u64 v[4:5], s[4:5], 0, v[2:3]
	v_lshlrev_b32_e32 v64, 1, v92
	v_lshl_add_u64 v[4:5], v[4:5], 0, v[64:65]
	global_load_dwordx2 v[6:7], v[4:5], off offset:768
	global_load_dwordx2 v[8:9], v[4:5], off offset:800
	global_load_dwordx2 v[10:11], v[4:5], off offset:832
	s_nop 0
	global_load_dwordx2 v[4:5], v[4:5], off offset:864
	s_waitcnt lgkmcnt(0)
	v_add_f32_e32 v12, v0, v1
	v_div_scale_f32 v13, s[4:5], v12, v12, 1.0
	v_rcp_f32_e32 v14, v13
	v_div_scale_f32 v15, vcc, 1.0, v12, 1.0
	v_fma_f32 v0, -v13, v14, 1.0
	v_fmac_f32_e32 v14, v0, v14
	v_lshl_add_u64 v[0:1], s[2:3], 0, v[2:3]
	v_mul_f32_e32 v2, v15, v14
	v_fma_f32 v3, -v13, v2, v15
	v_fmac_f32_e32 v2, v3, v14
	v_fma_f32 v3, -v13, v2, v15
	v_div_fmas_f32 v2, v3, v14, v2
	v_div_fixup_f32 v2, v2, v12, 1.0
	v_mul_f32_e32 v3, v52, v2
	v_mul_f32_e32 v12, v53, v2
	v_mul_f32_e32 v13, v54, v2
	v_mul_f32_e32 v14, v55, v2
	v_mul_f32_e32 v15, v44, v2
	v_mul_f32_e32 v16, v45, v2
	v_mul_f32_e32 v17, v46, v2
	v_mul_f32_e32 v18, v47, v2
	v_mul_f32_e32 v19, v48, v2
	s_waitcnt vmcnt(7)
	v_mul_f32_e32 v20, v49, v2
	v_mul_f32_e32 v21, v50, v2
	v_mul_f32_e32 v22, v51, v2
	v_mul_f32_e32 v23, v40, v2
	s_waitcnt vmcnt(6)
	v_mul_f32_e32 v24, v41, v2
	v_mul_f32_e32 v25, v42, v2
	v_mul_f32_e32 v2, v43, v2
	v_lshl_add_u64 v[0:1], v[0:1], 0, v[64:65]
	s_waitcnt vmcnt(3)
	v_lshlrev_b32_e32 v26, 16, v6
	v_and_b32_e32 v6, 0xffff0000, v6
	v_lshlrev_b32_e32 v27, 16, v7
	v_and_b32_e32 v7, 0xffff0000, v7
	s_waitcnt vmcnt(2)
	v_lshlrev_b32_e32 v28, 16, v8
	v_and_b32_e32 v8, 0xffff0000, v8
	v_lshlrev_b32_e32 v29, 16, v9
	v_and_b32_e32 v9, 0xffff0000, v9
	s_waitcnt vmcnt(1)
	v_lshlrev_b32_e32 v30, 16, v10
	v_and_b32_e32 v10, 0xffff0000, v10
	s_waitcnt vmcnt(0)
	v_lshlrev_b32_e32 v33, 16, v5
	v_and_b32_e32 v5, 0xffff0000, v5
	v_mul_f32_e32 v3, v3, v26
	v_lshlrev_b32_e32 v31, 16, v11
	v_and_b32_e32 v11, 0xffff0000, v11
	v_lshlrev_b32_e32 v32, 16, v4
	v_and_b32_e32 v4, 0xffff0000, v4
	v_mul_f32_e32 v6, v12, v6
	v_mul_f32_e32 v12, v13, v27
	v_mul_f32_e32 v7, v14, v7
	v_mul_f32_e32 v8, v16, v8
	v_mul_f32_e32 v9, v18, v9
	v_mul_f32_e32 v10, v20, v10
	v_mul_f32_e32 v20, v2, v5
	v_cvt_pk_bf16_f32 v2, v3, v6
	v_cvt_pk_bf16_f32 v3, v12, v7
	v_mul_f32_e32 v13, v15, v28
	v_mul_f32_e32 v14, v17, v29
	v_mul_f32_e32 v15, v19, v30
	v_mul_f32_e32 v16, v21, v31
	v_mul_f32_e32 v11, v22, v11
	v_mul_f32_e32 v17, v23, v32
	v_mul_f32_e32 v18, v24, v4
	v_mul_f32_e32 v19, v25, v33
	v_cvt_pk_bf16_f32 v4, v13, v8
	v_cvt_pk_bf16_f32 v5, v14, v9
	v_cvt_pk_bf16_f32 v6, v15, v10
	v_cvt_pk_bf16_f32 v7, v16, v11
	v_cvt_pk_bf16_f32 v8, v17, v18
	v_cvt_pk_bf16_f32 v9, v19, v20
	global_store_dwordx2 v[0:1], v[2:3], off offset:768 nt
	global_store_dwordx2 v[0:1], v[4:5], off offset:800 nt
	global_store_dwordx2 v[0:1], v[6:7], off offset:832 nt
	global_store_dwordx2 v[0:1], v[8:9], off offset:864 nt
